# stack2 plus one LDS wait per two MFMAs in the hot P10 P.V block
# speedup vs baseline: 1.0063x; 1.0001x over previous
.Lfa_maxjoin:
	v_mov_b32_e32 v168, v144
	v_mov_b32_e32 v169, v144
	s_nop 1
	v_permlane32_swap_b32_e32 v168, v169
	v_max_f32_e32 v144, v168, v169
	v_cmp_lt_f32_e32 vcc, s79, v144
	s_cbranch_vccnz .Lfa_rare
	s_waitcnt lgkmcnt(2)
	v_mfma_f32_32x32x16_bf16 v[48:63], v[232:235], v[216:219], v[48:63]
	ds_read_b128 v[232:235], v211 offset:51232
	v_exp_f32_e32 v168, v80
	v_exp_f32_e32 v169, v81
	v_mfma_f32_32x32x16_bf16 v[32:47], v[202:205], v[216:219], v[32:47]
	ds_read_b128 v[202:205], v211 offset:55840
	v_exp_f32_e32 v170, v82
	v_exp_f32_e32 v171, v83
	v_add_f32_e32 v194, v194, v168
	v_add_f32_e32 v195, v195, v169
	s_waitcnt lgkmcnt(2)
	v_mfma_f32_32x32x16_bf16 v[16:31], v[206:209], v[216:219], v[16:31]
	ds_read_b128 v[206:209], v211 offset:60448
	v_exp_f32_e32 v172, v84
	v_exp_f32_e32 v173, v85
	v_add_f32_e32 v196, v196, v170
	v_add_f32_e32 v197, v197, v171
	v_mfma_f32_32x32x16_bf16 v[0:15], v[244:247], v[216:219], v[0:15]
	ds_read_b128 v[244:247], v211 offset:65056
	v_exp_f32_e32 v174, v86
	v_exp_f32_e32 v175, v87
	v_add_f32_e32 v194, v194, v172
	v_add_f32_e32 v195, v195, v173
	s_waitcnt lgkmcnt(2)
	v_mfma_f32_32x32x16_bf16 v[48:63], v[232:235], v[220:223], v[48:63]
	ds_read_b128 v[232:235], v211 offset:51264
	v_exp_f32_e32 v176, v88
	v_exp_f32_e32 v177, v89
	v_add_f32_e32 v196, v196, v174
	v_add_f32_e32 v197, v197, v175
	v_cvt_pk_bf16_f32 v216, v168, v169
	v_mfma_f32_32x32x16_bf16 v[32:47], v[202:205], v[220:223], v[32:47]
	ds_read_b128 v[202:205], v211 offset:55872
	v_exp_f32_e32 v178, v90
	v_exp_f32_e32 v179, v91
	v_add_f32_e32 v194, v194, v176
	v_add_f32_e32 v195, v195, v177
	v_cvt_pk_bf16_f32 v217, v170, v171
	s_waitcnt lgkmcnt(2)
	v_mfma_f32_32x32x16_bf16 v[16:31], v[206:209], v[220:223], v[16:31]
	ds_read_b128 v[206:209], v211 offset:60480
	v_exp_f32_e32 v180, v92
	v_exp_f32_e32 v181, v93
	v_add_f32_e32 v196, v196, v178
	v_add_f32_e32 v197, v197, v179
	v_cvt_pk_bf16_f32 v218, v172, v173
	v_mfma_f32_32x32x16_bf16 v[0:15], v[244:247], v[220:223], v[0:15]
	ds_read_b128 v[244:247], v211 offset:65088
	v_exp_f32_e32 v182, v94
	v_exp_f32_e32 v183, v95
	v_add_f32_e32 v194, v194, v180
	v_add_f32_e32 v195, v195, v181
	v_cvt_pk_bf16_f32 v219, v174, v175
	s_waitcnt lgkmcnt(2)
	v_mfma_f32_32x32x16_bf16 v[48:63], v[232:235], v[224:227], v[48:63]
	ds_read_b128 v[232:235], v211 offset:51296
	v_exp_f32_e32 v64, v64
	v_exp_f32_e32 v65, v65
	v_add_f32_e32 v196, v196, v182
	v_add_f32_e32 v197, v197, v183
	v_cvt_pk_bf16_f32 v220, v176, v177
	v_mfma_f32_32x32x16_bf16 v[32:47], v[202:205], v[224:227], v[32:47]
	ds_read_b128 v[202:205], v211 offset:55904
	v_exp_f32_e32 v66, v66
	v_exp_f32_e32 v67, v67
	v_add_f32_e32 v194, v194, v64
	v_add_f32_e32 v195, v195, v65
	v_cvt_pk_bf16_f32 v221, v178, v179
	s_waitcnt lgkmcnt(2)
	v_mfma_f32_32x32x16_bf16 v[16:31], v[206:209], v[224:227], v[16:31]
	ds_read_b128 v[206:209], v211 offset:60512
	v_exp_f32_e32 v68, v68
	v_exp_f32_e32 v69, v69
	v_add_f32_e32 v196, v196, v66
	v_add_f32_e32 v197, v197, v67
	v_cvt_pk_bf16_f32 v222, v180, v181
	v_mfma_f32_32x32x16_bf16 v[0:15], v[244:247], v[224:227], v[0:15]
	ds_read_b128 v[244:247], v211 offset:65120
	v_exp_f32_e32 v70, v70
	v_exp_f32_e32 v71, v71
	v_add_f32_e32 v194, v194, v68
	v_add_f32_e32 v195, v195, v69
	v_cvt_pk_bf16_f32 v223, v182, v183
	s_waitcnt lgkmcnt(2)
	v_mfma_f32_32x32x16_bf16 v[48:63], v[232:235], v[228:231], v[48:63]
	v_exp_f32_e32 v72, v72
	v_exp_f32_e32 v73, v73
	v_add_f32_e32 v196, v196, v70
	v_add_f32_e32 v197, v197, v71
	v_cvt_pk_bf16_f32 v224, v64, v65
	v_mfma_f32_32x32x16_bf16 v[32:47], v[202:205], v[228:231], v[32:47]
	v_exp_f32_e32 v74, v74
	v_exp_f32_e32 v75, v75
	v_add_f32_e32 v194, v194, v72
	v_add_f32_e32 v195, v195, v73
	v_cvt_pk_bf16_f32 v225, v66, v67
	s_waitcnt lgkmcnt(0)
	v_mfma_f32_32x32x16_bf16 v[16:31], v[206:209], v[228:231], v[16:31]
	v_exp_f32_e32 v76, v76
	v_exp_f32_e32 v77, v77
	v_add_f32_e32 v196, v196, v74
	v_add_f32_e32 v197, v197, v75
	v_cvt_pk_bf16_f32 v226, v68, v69
	v_mfma_f32_32x32x16_bf16 v[0:15], v[244:247], v[228:231], v[0:15]
	v_exp_f32_e32 v78, v78
	v_exp_f32_e32 v79, v79
	v_add_f32_e32 v194, v194, v76
	v_add_f32_e32 v195, v195, v77
	v_cvt_pk_bf16_f32 v227, v70, v71
	v_cvt_pk_bf16_f32 v228, v72, v73
	v_add_f32_e32 v196, v196, v78
	v_add_f32_e32 v197, v197, v79
	v_cvt_pk_bf16_f32 v229, v74, v75
	v_cvt_pk_bf16_f32 v230, v76, v77
	v_cvt_pk_bf16_f32 v231, v78, v79
	s_mov_b32 s88, 1
	s_branch .LBB0_1332
